# speedup vs baseline: 1.0248x; 1.0017x over previous
; __device__ __forceinline__ void finishSM(f32x16& p0, f32x16& p1, float alpha, float& l_reg, bf16x8& pa0, bf16x8& pa1, bf16x8& pa2, bf16x8& pa3) {
; #pragma unroll
;     for (int r = 0; r < 16; ++r) p1[r] = __builtin_amdgcn_exp2f(p1[r]);
;     float ps = 0;
; #pragma unroll
;     for (int r = 0; r < 16; ++r) ps += p0[r];
; #pragma unroll
;     for (int r = 0; r < 16; ++r) ps += p1[r];
;     { auto rr = __builtin_amdgcn_permlane32_swap(__float_as_uint(ps), __float_as_uint(ps), false, false);
;       ps = __uint_as_float(rr[0]) + __uint_as_float(rr[1]); }
;     l_reg = l_reg * alpha + ps;
;     ...
;     PK4(p0, 0, pa0); PK4(p0, 8, pa1); PK4(p1, 0, pa2); PK4(p1, 8, pa3);
;     ...
; }
; template <int KB>
; __device__ __forceinline__ void qkt(f32x16& p0, f32x16& p1, const char* lds, int r32, int hi, const bf16x8* qr) {
;     p0 = f32x16{}; p1 = f32x16{};
;     const char* kb = lds + AO_K + KB * SHM_K + KSWZ(r32, hi * 16); const char* rb = lds + AO_R + KB * SHM_R + RSWZ(r32, hi * 16);
; #pragma unroll
;     for (int d0 = 0; d0 < 8; ++d0) { const char* a = kb + d0 * 32;
;         bf16x8 b0 = *reinterpret_cast<const bf16x8*>(a);
;         bf16x8 b1 = *reinterpret_cast<const bf16x8*>(a + 32 * KPITCH);
;         p0 = __builtin_amdgcn_mfma_f32_32x32x16_bf16(b0, qr[d0], p0, 0, 0, 0);
;         p1 = __builtin_amdgcn_mfma_f32_32x32x16_bf16(b1, qr[d0], p1, 0, 0, 0); }
; #pragma unroll
;     for (int d0 = 0; d0 < 4; ++d0) { const char* a = rb + d0 * 32;
;         bf16x8 b0 = *reinterpret_cast<const bf16x8*>(a);
;         bf16x8 b1 = *reinterpret_cast<const bf16x8*>(a + 32 * RPITCH);
;         p0 = __builtin_amdgcn_mfma_f32_32x32x16_bf16(b0, qr[8 + d0], p0, 0, 0, 0);
;         p1 = __builtin_amdgcn_mfma_f32_32x32x16_bf16(b1, qr[8 + d0], p1, 0, 0, 0); }
; }
.LBB0_408:
	ds_read_b128 v[70:73], v200 offset:50176
	ds_read_b128 v[66:69], v200 offset:58880
	ds_read_b128 v[178:181], v200 offset:50208
	ds_read_b128 v[212:215], v200 offset:58912
	ds_read_b128 v[242:245], v200 offset:50240
	ds_read_b128 v[246:249], v200 offset:58944
	v_exp_f32_e32 v166, v166
	v_exp_f32_e32 v175, v175
	v_exp_f32_e32 v167, v167
	v_exp_f32_e32 v176, v176
	s_waitcnt lgkmcnt(4)
	v_mfma_f32_32x32x16_bf16 v[82:97], v[70:73], v[142:145], 0
	v_exp_f32_e32 v168, v168
	v_exp_f32_e32 v177, v177
	v_exp_f32_e32 v169, v169
	v_exp_f32_e32 v174, v174
	v_mfma_f32_32x32x16_bf16 v[66:81], v[66:69], v[142:145], 0
	v_exp_f32_e32 v165, v165
	v_exp_f32_e32 v170, v170
	v_exp_f32_e32 v171, v171
	s_waitcnt lgkmcnt(2)
	v_mfma_f32_32x32x16_bf16 v[66:81], v[212:215], v[138:141], v[66:81]
	v_exp_f32_e32 v172, v172
	v_exp_f32_e32 v162, v162
	v_exp_f32_e32 v164, v164
	v_exp_f32_e32 v163, v163
	v_mfma_f32_32x32x16_bf16 v[82:97], v[178:181], v[138:141], v[82:97]
	ds_read_b128 v[178:181], v200 offset:50272
	ds_read_b128 v[212:215], v200 offset:58976
	v_exp_f32_e32 v173, v173
	v_exp_f32_e32 v0, v160
	v_exp_f32_e32 v160, v161
	s_waitcnt lgkmcnt(2)
	v_mfma_f32_32x32x16_bf16 v[66:81], v[246:249], v[134:137], v[66:81]
	v_add_f32_e32 v161, v175, v166
	v_add_f32_e32 v161, v167, v161
	v_add_f32_e32 v161, v176, v161
	v_mfma_f32_32x32x16_bf16 v[82:97], v[242:245], v[134:137], v[82:97]
	ds_read_b128 v[242:245], v200 offset:50304
	ds_read_b128 v[246:249], v200 offset:59008
	v_add_f32_e32 v161, v168, v161
	v_add_f32_e32 v161, v177, v161
	v_add_f32_e32 v161, v169, v161
	s_waitcnt lgkmcnt(2)
	v_mfma_f32_32x32x16_bf16 v[66:81], v[212:215], v[130:133], v[66:81]
	v_add_f32_e32 v161, v174, v161
	v_add_f32_e32 v161, v165, v161
	v_add_f32_e32 v161, v170, v161
	v_add_f32_e32 v161, v171, v161
	v_mfma_f32_32x32x16_bf16 v[82:97], v[178:181], v[130:133], v[82:97]
	ds_read_b128 v[178:181], v200 offset:50336
	ds_read_b128 v[212:215], v200 offset:59040
	v_add_f32_e32 v161, v172, v161
	v_add_f32_e32 v161, v162, v161
	v_add_f32_e32 v161, v164, v161
	v_exp_f32_e32 v158, v158
	s_waitcnt lgkmcnt(2)
	v_mfma_f32_32x32x16_bf16 v[66:81], v[246:249], v[126:129], v[66:81]
	v_add_f32_e32 v161, v163, v161
	v_exp_f32_e32 v159, v159
	v_add_f32_e32 v161, v173, v161
	v_mfma_f32_32x32x16_bf16 v[82:97], v[242:245], v[126:129], v[82:97]
	ds_read_b128 v[242:245], v200 offset:50368
	ds_read_b128 v[246:249], v200 offset:59072
	v_exp_f32_e32 v154, v154
	v_add_f32_e32 v161, v0, v161
	v_exp_f32_e32 v155, v155
	v_add_f32_e32 v161, v160, v161
	s_waitcnt lgkmcnt(2)
	v_mfma_f32_32x32x16_bf16 v[66:81], v[212:215], v[122:125], v[66:81]
	v_exp_f32_e32 v150, v150
	v_add_f32_e32 v161, v158, v161
	v_exp_f32_e32 v151, v151
	v_mfma_f32_32x32x16_bf16 v[82:97], v[178:181], v[122:125], v[82:97]
	ds_read_b128 v[178:181], v200 offset:50400
	ds_read_b128 v[212:215], v200 offset:59104
	v_add_f32_e32 v161, v159, v161
	v_exp_f32_e32 v146, v146
	v_add_f32_e32 v161, v154, v161
	v_exp_f32_e32 v147, v147
	s_waitcnt lgkmcnt(2)
	v_mfma_f32_32x32x16_bf16 v[66:81], v[246:249], v[118:121], v[66:81]
	v_add_f32_e32 v161, v155, v161
	v_exp_f32_e32 v156, v156
	v_add_f32_e32 v161, v150, v161
	v_mfma_f32_32x32x16_bf16 v[82:97], v[242:245], v[118:121], v[82:97]
	ds_read_b128 v[242:245], v205
	ds_read_b128 v[246:249], v205 offset:4608
	v_exp_f32_e32 v157, v157
	v_add_f32_e32 v161, v151, v161
	v_exp_f32_e32 v152, v152
	v_add_f32_e32 v161, v146, v161
	s_waitcnt lgkmcnt(2)
	v_mfma_f32_32x32x16_bf16 v[66:81], v[212:215], v[110:113], v[66:81]
	v_exp_f32_e32 v153, v153
	v_add_f32_e32 v161, v147, v161
	v_exp_f32_e32 v148, v148
	v_add_f32_e32 v161, v156, v161
	v_mfma_f32_32x32x16_bf16 v[82:97], v[178:181], v[110:113], v[82:97]
	ds_read_b128 v[178:181], v205 offset:32
	ds_read_b128 v[212:215], v205 offset:4640
	v_exp_f32_e32 v149, v149
	v_add_f32_e32 v161, v157, v161
	v_add_f32_e32 v161, v152, v161
	s_waitcnt lgkmcnt(2)
	v_mfma_f32_32x32x16_bf16 v[66:81], v[246:249], v[114:117], v[66:81]
	v_add_f32_e32 v161, v153, v161
	v_add_f32_e32 v161, v148, v161
	v_add_f32_e32 v211, v149, v161
	v_cvt_pk_bf16_f32 v166, v166, v175
	v_mfma_f32_32x32x16_bf16 v[82:97], v[242:245], v[114:117], v[82:97]
	ds_read_b128 v[242:245], v205 offset:64
	ds_read_b128 v[246:249], v205 offset:4672
	v_cvt_pk_bf16_f32 v167, v167, v176
	v_cvt_pk_bf16_f32 v168, v168, v177
	v_cvt_pk_bf16_f32 v169, v169, v174
	s_waitcnt lgkmcnt(2)
	v_mfma_f32_32x32x16_bf16 v[82:97], v[178:181], v[106:109], v[82:97]
	v_cvt_pk_bf16_f32 v170, v165, v170
	v_cvt_pk_bf16_f32 v171, v171, v172
	v_cvt_pk_bf16_f32 v172, v162, v164
	v_cvt_pk_bf16_f32 v173, v163, v173
	v_mfma_f32_32x32x16_bf16 v[66:81], v[212:215], v[106:109], v[66:81]
	ds_read_b128 v[178:181], v205 offset:96
	ds_read_b128 v[212:215], v205 offset:4704
	v_cvt_pk_bf16_f32 v174, v0, v160
	v_cvt_pk_bf16_f32 v175, v158, v159
	v_cvt_pk_bf16_f32 v176, v154, v155
	s_waitcnt lgkmcnt(2)
	v_mfma_f32_32x32x16_bf16 v[82:97], v[242:245], v[102:105], v[82:97]
	v_cvt_pk_bf16_f32 v177, v150, v151
	v_permlane32_swap_b32_e32 v166, v168
	v_permlane32_swap_b32_e32 v167, v169
	v_permlane32_swap_b32_e32 v170, v172
	v_mfma_f32_32x32x16_bf16 v[66:81], v[246:249], v[102:105], v[66:81]
	v_permlane32_swap_b32_e32 v171, v173
	v_permlane32_swap_b32_e32 v174, v176
	v_permlane32_swap_b32_e32 v175, v177
	s_waitcnt lgkmcnt(0)
	v_mfma_f32_32x32x16_bf16 v[82:97], v[178:181], v[98:101], v[82:97]
	v_cvt_pk_bf16_f32 v178, v146, v147
	v_cvt_pk_bf16_f32 v179, v156, v157
	v_cvt_pk_bf16_f32 v180, v152, v153
	v_cvt_pk_bf16_f32 v181, v148, v149
	s_nop 0
	v_permlane32_swap_b32_e32 v178, v180
	v_mfma_f32_32x32x16_bf16 v[66:81], v[212:215], v[98:101], v[66:81]
	v_mov_b32_e32 v212, v211
	s_nop 1
	v_permlane32_swap_b32_e32 v211, v212
	v_permlane32_swap_b32_e32 v179, v181
	ds_read_b64_tr_b16 v[214:215], v194 offset:0
	ds_read_b64_tr_b16 v[216:217], v194 offset:0x800
	ds_read_b64_tr_b16 v[218:219], v194 offset:0x1000
	ds_read_b64_tr_b16 v[220:221], v194 offset:0x1800
	ds_read_b64_tr_b16 v[222:223], v194 offset:0x2000
	ds_read_b64_tr_b16 v[224:225], v194 offset:0x2800
	ds_read_b64_tr_b16 v[226:227], v194 offset:0x3000
	ds_read_b64_tr_b16 v[228:229], v194 offset:0x3800
	s_add_u32 s74, s76, s96
	s_addc_u32 s75, s77, s97
	s_add_u32 s80, s88, s96
	s_addc_u32 s81, s89, s97
	s_add_u32 s8, s74, 0x1b988000
	s_addc_u32 s9, s75, 0
	s_add_u32 s10, s74, 0x1b98a000
	s_addc_u32 s11, s75, 0
	s_add_u32 s12, s80, 0x18884000
	s_addc_u32 s13, s81, 0
	s_add_u32 s14, s74, 0x1d988000
	s_addc_u32 s15, s75, 0
	s_add_u32 s16, s74, 0x1d98a000
	s_addc_u32 s17, s75, 0
	global_load_dwordx4 v[154:157], v201, s[8:9]
	global_load_dwordx4 v[158:161], v201, s[10:11]
	global_load_dwordx4 v[162:165], v199, s[12:13]
	global_load_dwordx4 v[146:149], v201, s[14:15]
	global_load_dwordx4 v[150:153], v201, s[16:17]
	s_sub_i32 s6, s70, 64
	s_cmp_le_i32 s6, s33
	s_cbranch_scc1 .LBB0_410
; __device__ __forceinline__ void mask_tile(f32x16& p0, f32x16& p1, int dq) {
;     const float NEG = -__builtin_inff();
; #pragma unroll
;     for (int r = 0; r < 16; ++r) { const int c = (r & 3) + 8 * (r >> 2);
;         if (dq - c < 0) p0[r] = NEG;
;         if (dq - c - 32 < 0) p1[r] = NEG; }
; }
; __device__ __forceinline__ void partialSM(f32x16& p0, f32x16& p1, float& m_reg, float& mn, float& alpha) {
;     float pmax = p0[0];
; #pragma unroll
;     for (int r = 1; r < 16; ++r) pmax = fmaxf(pmax, p0[r]);
; #pragma unroll
;     for (int r = 0; r < 16; ++r) pmax = fmaxf(pmax, p1[r]);
;     { auto rr = __builtin_amdgcn_permlane32_swap(__float_as_uint(pmax), __float_as_uint(pmax), false, false);
;       pmax = fmaxf(__uint_as_float(rr[0]), __uint_as_float(rr[1])); }
; template <int VB>
; __device__ __forceinline__ void pv_tile(f32x16* o, int vb0, bf16x8 pa0, bf16x8 pa1, bf16x8 pa2, bf16x8 pa3) {
;     ...
;     PV_D0(0); PV_D0(1); PV_D0(2); PV_D0(3);
	v_add_u32_e32 v0, 64, v209
	v_cmp_gt_i32_e64 s[64:65], 26, v0
	v_cmp_gt_i32_e64 s[66:67], 27, v0
	v_cmp_gt_i32_e64 s[62:63], 25, v0
	s_and_b64 s[64:65], s[66:67], s[64:65]
	v_cmp_gt_i32_e64 s[60:61], 24, v0
	s_and_b64 s[62:63], s[64:65], s[62:63]
	v_cmp_gt_i32_e64 s[58:59], 19, v0
	s_and_b64 s[60:61], s[62:63], s[60:61]
	v_cmp_gt_i32_e64 s[56:57], 18, v0
	s_and_b64 s[58:59], s[60:61], s[58:59]
	v_cmp_gt_i32_e64 s[54:55], 17, v0
	s_and_b64 s[56:57], s[58:59], s[56:57]
	v_cmp_gt_i32_e64 s[52:53], 16, v0
	s_and_b64 s[54:55], s[56:57], s[54:55]
	v_cmp_gt_i32_e64 s[50:51], 11, v0
	s_and_b64 s[52:53], s[54:55], s[52:53]
	v_cmp_gt_i32_e64 s[48:49], 10, v0
	s_and_b64 s[50:51], s[52:53], s[50:51]
	v_cmp_gt_i32_e64 s[46:47], 9, v0
	s_and_b64 s[48:49], s[50:51], s[48:49]
	v_cmp_gt_i32_e64 s[44:45], 8, v0
	s_and_b64 s[46:47], s[48:49], s[46:47]
	v_cmp_gt_i32_e64 s[42:43], 3, v0
	s_and_b64 s[44:45], s[46:47], s[44:45]
	v_cmp_gt_i32_e64 s[40:41], 2, v0
	s_and_b64 s[42:43], s[44:45], s[42:43]
	v_cmp_gt_i32_e64 s[38:39], 1, v0
	s_and_b64 s[40:41], s[42:43], s[40:41]
	v_cmp_gt_i32_e64 s[36:37], 0, v0
	s_and_b64 s[38:39], s[40:41], s[38:39]
	s_and_b64 s[36:37], s[38:39], s[36:37]
	v_cmp_gt_i32_e64 s[34:35], 58, v0
	v_cndmask_b32_e64 v82, v82, v186, s[36:37]
	v_cmp_gt_i32_e64 s[36:37], 59, v0
	v_cmp_gt_i32_e64 s[30:31], 57, v0
	s_and_b64 s[34:35], s[36:37], s[34:35]
	v_cmp_gt_i32_e64 s[28:29], 56, v0
	s_and_b64 s[30:31], s[34:35], s[30:31]
	v_cmp_gt_i32_e64 s[26:27], 51, v0
	s_and_b64 s[28:29], s[30:31], s[28:29]
	v_cmp_gt_i32_e64 s[24:25], 50, v0
	s_and_b64 s[26:27], s[28:29], s[26:27]
	v_cmp_gt_i32_e64 s[22:23], 49, v0
	s_and_b64 s[24:25], s[26:27], s[24:25]
	v_cmp_gt_i32_e64 s[20:21], 48, v0
	s_and_b64 s[22:23], s[24:25], s[22:23]
	v_cmp_gt_i32_e64 s[18:19], 43, v0
	s_and_b64 s[20:21], s[22:23], s[20:21]
	v_cmp_gt_i32_e64 s[16:17], 42, v0
	s_and_b64 s[18:19], s[20:21], s[18:19]
	v_cmp_gt_i32_e64 s[14:15], 41, v0
	s_and_b64 s[16:17], s[18:19], s[16:17]
	v_cmp_gt_i32_e64 s[12:13], 40, v0
	s_and_b64 s[14:15], s[16:17], s[14:15]
	v_cmp_gt_i32_e64 s[10:11], 35, v0
	s_and_b64 s[12:13], s[14:15], s[12:13]
	v_cmp_gt_i32_e64 s[8:9], 34, v0
	s_and_b64 s[10:11], s[12:13], s[10:11]
	v_cmp_gt_i32_e64 s[6:7], 33, v0
	s_and_b64 s[8:9], s[10:11], s[8:9]
	v_cmp_gt_i32_e32 vcc, 32, v0
	s_and_b64 s[6:7], s[8:9], s[6:7]
	s_and_b64 vcc, s[6:7], vcc
	v_cndmask_b32_e64 v97, v97, v186, s[66:67]
	v_cndmask_b32_e64 v96, v96, v186, s[64:65]
	v_cndmask_b32_e64 v95, v95, v186, s[62:63]
	v_cndmask_b32_e64 v94, v94, v186, s[60:61]
	v_cndmask_b32_e64 v93, v93, v186, s[58:59]
	v_cndmask_b32_e64 v92, v92, v186, s[56:57]
	v_cndmask_b32_e64 v91, v91, v186, s[54:55]
	v_cndmask_b32_e64 v90, v90, v186, s[52:53]
	v_cndmask_b32_e64 v89, v89, v186, s[50:51]
	v_cndmask_b32_e64 v88, v88, v186, s[48:49]
	v_cndmask_b32_e64 v87, v87, v186, s[46:47]
	v_cndmask_b32_e64 v86, v86, v186, s[44:45]
	v_cndmask_b32_e64 v85, v85, v186, s[42:43]
	v_cndmask_b32_e64 v84, v84, v186, s[40:41]
	v_cndmask_b32_e64 v83, v83, v186, s[38:39]
	v_cndmask_b32_e64 v81, v81, v186, s[36:37]
	v_cndmask_b32_e64 v80, v80, v186, s[34:35]
	v_cndmask_b32_e64 v79, v79, v186, s[30:31]
	v_cndmask_b32_e64 v78, v78, v186, s[28:29]
	v_cndmask_b32_e64 v77, v77, v186, s[26:27]
	v_cndmask_b32_e64 v76, v76, v186, s[24:25]
	v_cndmask_b32_e64 v75, v75, v186, s[22:23]
	v_cndmask_b32_e64 v74, v74, v186, s[20:21]
	v_cndmask_b32_e64 v73, v73, v186, s[18:19]
	v_cndmask_b32_e64 v72, v72, v186, s[16:17]
	v_cndmask_b32_e64 v71, v71, v186, s[14:15]
	v_cndmask_b32_e64 v70, v70, v186, s[12:13]
	v_cndmask_b32_e64 v69, v69, v186, s[10:11]
	v_cndmask_b32_e64 v68, v68, v186, s[8:9]
	v_cndmask_b32_e64 v67, v67, v186, s[6:7]
	v_cndmask_b32_e32 v66, v66, v186, vcc
.LBB0_410:
	s_nop 0
	s_waitcnt lgkmcnt(6)
	v_mfma_f32_32x32x16_bf16 v[50:65], v[166:169], v[214:217], v[50:65]
	ds_read_b64_tr_b16 v[214:215], v194 offset:0x200
	ds_read_b64_tr_b16 v[216:217], v194 offset:0xa00
	v_max_f32_e32 v0, v82, v83
	s_waitcnt lgkmcnt(6)
	v_mfma_f32_32x32x16_bf16 v[50:65], v[170:173], v[218:221], v[50:65]
	ds_read_b64_tr_b16 v[218:219], v194 offset:0x1200
	ds_read_b64_tr_b16 v[220:221], v194 offset:0x1a00
	v_max3_f32 v0, v0, v84, v85
	v_max3_f32 v0, v0, v86, v87
	s_waitcnt lgkmcnt(6)
	v_mfma_f32_32x32x16_bf16 v[50:65], v[174:177], v[222:225], v[50:65]
	ds_read_b64_tr_b16 v[222:223], v194 offset:0x2200
	ds_read_b64_tr_b16 v[224:225], v194 offset:0x2a00
	v_max3_f32 v0, v0, v88, v89
	v_max3_f32 v0, v0, v90, v91
	s_waitcnt lgkmcnt(6)
	v_mfma_f32_32x32x16_bf16 v[50:65], v[178:181], v[226:229], v[50:65]
	ds_read_b64_tr_b16 v[226:227], v194 offset:0x3200
	ds_read_b64_tr_b16 v[228:229], v194 offset:0x3a00
	v_max3_f32 v0, v0, v92, v93
	v_max3_f32 v0, v0, v94, v95
	v_max3_f32 v0, v0, v96, v97
	s_waitcnt lgkmcnt(6)
	v_mfma_f32_32x32x16_bf16 v[34:49], v[166:169], v[214:217], v[34:49]
	ds_read_b64_tr_b16 v[214:215], v194 offset:0x400
	ds_read_b64_tr_b16 v[216:217], v194 offset:0xc00
	v_max3_f32 v0, v0, v66, v67
	v_max3_f32 v0, v0, v68, v69
	s_waitcnt lgkmcnt(6)
	v_mfma_f32_32x32x16_bf16 v[34:49], v[170:173], v[218:221], v[34:49]
	ds_read_b64_tr_b16 v[218:219], v194 offset:0x1400
	ds_read_b64_tr_b16 v[220:221], v194 offset:0x1c00
	v_max3_f32 v0, v0, v70, v71
	v_max3_f32 v0, v0, v72, v73
	s_waitcnt lgkmcnt(6)
	v_mfma_f32_32x32x16_bf16 v[34:49], v[174:177], v[222:225], v[34:49]
	ds_read_b64_tr_b16 v[222:223], v194 offset:0x2400
	ds_read_b64_tr_b16 v[224:225], v194 offset:0x2c00
	v_max3_f32 v0, v0, v74, v75
	v_max3_f32 v0, v0, v76, v77
	v_max3_f32 v0, v0, v78, v79
	s_waitcnt lgkmcnt(6)
; __device__ __forceinline__ void partialSM(f32x16& p0, f32x16& p1, float& m_reg, float& mn, float& alpha) {
;     float pmax = p0[0];
; #pragma unroll
;     for (int r = 1; r < 16; ++r) pmax = fmaxf(pmax, p0[r]);
; #pragma unroll
;     for (int r = 0; r < 16; ++r) pmax = fmaxf(pmax, p1[r]);
;     { auto rr = __builtin_amdgcn_permlane32_swap(__float_as_uint(pmax), __float_as_uint(pmax), false, false);
;       pmax = fmaxf(__uint_as_float(rr[0]), __uint_as_float(rr[1])); }
;     constexpr float C2 = 1.4426950408889634f * ASCALE;
;     if (__builtin_expect(__all((pmax - m_reg) * ASCALE <= ATHR), 1)) { mn = m_reg; alpha = 1.f; }
;     else { mn = fmaxf(m_reg, pmax); alpha = __builtin_amdgcn_exp2f((m_reg - mn) * C2); m_reg = mn; }
	v_mfma_f32_32x32x16_bf16 v[34:49], v[178:181], v[226:229], v[34:49]
	ds_read_b64_tr_b16 v[226:227], v194 offset:0x3400
	ds_read_b64_tr_b16 v[228:229], v194 offset:0x3c00
	v_max3_f32 v0, v0, v80, v81
	v_mov_b32_e32 v190, v0
	s_waitcnt lgkmcnt(6)
	v_mfma_f32_32x32x16_bf16 v[18:33], v[166:169], v[214:217], v[18:33]
	ds_read_b64_tr_b16 v[214:215], v194 offset:0x600
	ds_read_b64_tr_b16 v[216:217], v194 offset:0xe00
	v_permlane32_swap_b32_e32 v0, v190
	s_waitcnt lgkmcnt(6)
	v_mfma_f32_32x32x16_bf16 v[18:33], v[170:173], v[218:221], v[18:33]
	ds_read_b64_tr_b16 v[218:219], v194 offset:0x1600
	ds_read_b64_tr_b16 v[220:221], v194 offset:0x1e00
	v_max_f32_e32 v0, v0, v190
	s_waitcnt lgkmcnt(6)
	v_mfma_f32_32x32x16_bf16 v[18:33], v[174:177], v[222:225], v[18:33]
	ds_read_b64_tr_b16 v[222:223], v194 offset:0x2600
	ds_read_b64_tr_b16 v[224:225], v194 offset:0x2e00
	v_sub_f32_e32 v190, v0, v210
	s_waitcnt lgkmcnt(6)
	v_mfma_f32_32x32x16_bf16 v[18:33], v[178:181], v[226:229], v[18:33]
	ds_read_b64_tr_b16 v[226:227], v194 offset:0x3600
	ds_read_b64_tr_b16 v[228:229], v194 offset:0x3e00
	v_max_f32_e32 v0, v210, v0
	v_sub_f32_e32 v191, v210, v0
	s_waitcnt lgkmcnt(6)
	v_mfma_f32_32x32x16_bf16 v[2:17], v[166:169], v[214:217], v[2:17]
	s_waitcnt vmcnt(2)
	v_add_u32_e32 v192, 0x10800, v206
	ds_write_b128 v207, v[154:157] offset:32768
	ds_write_b128 v207, v[158:161] offset:41472
	ds_write_b128 v192, v[162:165]
	v_mul_f32_e32 v191, 0x3dd53b94, v191
	v_mul_f32_e32 v190, 0x3d93cd3a, v190
	v_exp_f32_e32 v191, v191
	s_waitcnt lgkmcnt(7)
	v_mfma_f32_32x32x16_bf16 v[2:17], v[170:173], v[218:221], v[2:17]
	s_mov_b32 s6, 0x41000000
	v_cmp_ge_f32_e32 vcc, s6, v190
	s_waitcnt lgkmcnt(5)
	v_mfma_f32_32x32x16_bf16 v[2:17], v[174:177], v[222:225], v[2:17]
	s_cmp_eq_u64 vcc, exec
	s_cselect_b64 s[6:7], -1, 0
	s_waitcnt lgkmcnt(3)
	v_mfma_f32_32x32x16_bf16 v[2:17], v[178:181], v[226:229], v[2:17]
	s_barrier
	s_waitcnt vmcnt(0)
	v_cndmask_b32_e64 v213, v191, 1.0, s[6:7]
	v_cmp_gt_f32_e32 vcc, 1.0, v213
	ds_write_b128 v202, v[146:149]
	ds_write_b128 v203, v[150:153]
	s_cbranch_vccz .LBB0_414
	s_and_saveexec_b64 s[8:9], s[4:5]
	ds_write_b32 v195, v213 offset:128
	s_or_b64 exec, exec, s[8:9]
	s_waitcnt lgkmcnt(0)
	ds_read_b128 v[166:169], v198 offset:224
	ds_read_b128 v[170:173], v198 offset:192
	ds_read_b128 v[174:177], v198 offset:160
	ds_read_b128 v[178:181], v198 offset:128
	s_waitcnt lgkmcnt(3)
	v_pk_mul_f32 v[64:65], v[64:65], v[168:169]
	s_waitcnt lgkmcnt(2)
	v_pk_mul_f32 v[60:61], v[60:61], v[172:173]
	s_waitcnt lgkmcnt(1)
	v_pk_mul_f32 v[56:57], v[56:57], v[176:177]
	s_waitcnt lgkmcnt(0)
	v_pk_mul_f32 v[52:53], v[52:53], v[180:181]
	v_pk_mul_f32 v[62:63], v[62:63], v[166:167]
	v_pk_mul_f32 v[58:59], v[58:59], v[170:171]
	v_pk_mul_f32 v[54:55], v[54:55], v[174:175]
	v_pk_mul_f32 v[50:51], v[50:51], v[178:179]
	v_pk_mul_f32 v[48:49], v[48:49], v[168:169]
	v_pk_mul_f32 v[44:45], v[44:45], v[172:173]
	v_pk_mul_f32 v[40:41], v[40:41], v[176:177]
	v_pk_mul_f32 v[36:37], v[36:37], v[180:181]
	v_pk_mul_f32 v[46:47], v[46:47], v[166:167]
	v_pk_mul_f32 v[42:43], v[42:43], v[170:171]
	v_pk_mul_f32 v[38:39], v[38:39], v[174:175]
	v_pk_mul_f32 v[34:35], v[34:35], v[178:179]
	v_pk_mul_f32 v[32:33], v[32:33], v[168:169]
	v_pk_mul_f32 v[28:29], v[28:29], v[172:173]
	v_pk_mul_f32 v[24:25], v[24:25], v[176:177]
	v_pk_mul_f32 v[20:21], v[20:21], v[180:181]
	v_pk_mul_f32 v[30:31], v[30:31], v[166:167]
	v_pk_mul_f32 v[26:27], v[26:27], v[170:171]
	v_pk_mul_f32 v[22:23], v[22:23], v[174:175]
	v_pk_mul_f32 v[18:19], v[18:19], v[178:179]
	v_pk_mul_f32 v[16:17], v[16:17], v[168:169]
	v_pk_mul_f32 v[12:13], v[12:13], v[172:173]
	v_pk_mul_f32 v[8:9], v[8:9], v[176:177]
	v_pk_mul_f32 v[4:5], v[4:5], v[180:181]
	v_pk_mul_f32 v[14:15], v[14:15], v[166:167]
	v_pk_mul_f32 v[10:11], v[10:11], v[170:171]
	v_pk_mul_f32 v[6:7], v[6:7], v[174:175]
	v_pk_mul_f32 v[2:3], v[2:3], v[178:179]
.LBB0_414:
	v_cndmask_b32_e64 v210, v0, v210, s[6:7]
	v_mul_f32_e32 v181, 0xbdd53b94, v210
	v_fmamk_f32 v166, v82, 0x3dd53b94, v181
	v_fmamk_f32 v180, v83, 0x3dd53b94, v181
	v_fmamk_f32 v167, v84, 0x3dd53b94, v181
	v_fmamk_f32 v179, v85, 0x3dd53b94, v181
	v_fmamk_f32 v168, v86, 0x3dd53b94, v181
	v_fmamk_f32 v178, v87, 0x3dd53b94, v181
	v_fmamk_f32 v169, v88, 0x3dd53b94, v181
	v_fmamk_f32 v177, v89, 0x3dd53b94, v181
	v_fmamk_f32 v170, v90, 0x3dd53b94, v181
	v_fmamk_f32 v176, v91, 0x3dd53b94, v181
	v_fmamk_f32 v171, v92, 0x3dd53b94, v181
	v_fmamk_f32 v175, v93, 0x3dd53b94, v181
	v_fmamk_f32 v172, v94, 0x3dd53b94, v181
	v_fmamk_f32 v174, v95, 0x3dd53b94, v181
	v_fmamk_f32 v0, v96, 0x3dd53b94, v181
	v_fmamk_f32 v173, v97, 0x3dd53b94, v181
	v_fmamk_f32 v223, v66, 0x3dd53b94, v181
	v_fmamk_f32 v224, v67, 0x3dd53b94, v181
	v_fmamk_f32 v225, v68, 0x3dd53b94, v181
	v_fmamk_f32 v226, v69, 0x3dd53b94, v181
	v_fmamk_f32 v227, v70, 0x3dd53b94, v181
	v_fmamk_f32 v216, v71, 0x3dd53b94, v181
	v_fmamk_f32 v217, v72, 0x3dd53b94, v181
	v_fmamk_f32 v218, v73, 0x3dd53b94, v181
	v_fmamk_f32 v219, v74, 0x3dd53b94, v181
	v_fmamk_f32 v220, v75, 0x3dd53b94, v181
	v_fmamk_f32 v221, v76, 0x3dd53b94, v181
	v_fmamk_f32 v222, v77, 0x3dd53b94, v181
	v_fmamk_f32 v215, v78, 0x3dd53b94, v181
	v_fmamk_f32 v228, v79, 0x3dd53b94, v181
	v_fmamk_f32 v229, v80, 0x3dd53b94, v181
	v_fmac_f32_e32 v181, 0x3dd53b94, v81
	s_waitcnt lgkmcnt(0)
	s_barrier
; __device__ __forceinline__ void finishSM(f32x16& p0, f32x16& p1, float alpha, float& l_reg, bf16x8& pa0, bf16x8& pa1, bf16x8& pa2, bf16x8& pa3) {
; #pragma unroll
;     for (int r = 0; r < 16; ++r) p1[r] = __builtin_amdgcn_exp2f(p1[r]);
;     float ps = 0;
; #pragma unroll
;     for (int r = 0; r < 16; ++r) ps += p0[r];
; #pragma unroll
;     for (int r = 0; r < 16; ++r) ps += p1[r];
;     { auto rr = __builtin_amdgcn_permlane32_swap(__float_as_uint(ps), __float_as_uint(ps), false, false);
;       ps = __uint_as_float(rr[0]) + __uint_as_float(rr[1]); }
;     l_reg = l_reg * alpha + ps;
;     ...
;     PK4(p0, 0, pa0); PK4(p0, 8, pa1); PK4(p1, 0, pa2); PK4(p1, 8, pa3);
;     ...
; }
; template <int KB>
; __device__ __forceinline__ void qkt(f32x16& p0, f32x16& p1, const char* lds, int r32, int hi, const bf16x8* qr) {
;     p0 = f32x16{}; p1 = f32x16{};
;     const char* kb = lds + AO_K + KB * SHM_K + KSWZ(r32, hi * 16); const char* rb = lds + AO_R + KB * SHM_R + RSWZ(r32, hi * 16);
; #pragma unroll
;     for (int d0 = 0; d0 < 8; ++d0) { const char* a = kb + d0 * 32;
;         bf16x8 b0 = *reinterpret_cast<const bf16x8*>(a);
;         bf16x8 b1 = *reinterpret_cast<const bf16x8*>(a + 32 * KPITCH);
;         p0 = __builtin_amdgcn_mfma_f32_32x32x16_bf16(b0, qr[d0], p0, 0, 0, 0);
;         p1 = __builtin_amdgcn_mfma_f32_32x32x16_bf16(b1, qr[d0], p1, 0, 0, 0); }
; #pragma unroll
;     for (int d0 = 0; d0 < 4; ++d0) { const char* a = rb + d0 * 32;
;         bf16x8 b0 = *reinterpret_cast<const bf16x8*>(a);
;         bf16x8 b1 = *reinterpret_cast<const bf16x8*>(a + 32 * RPITCH);
;         p0 = __builtin_amdgcn_mfma_f32_32x32x16_bf16(b0, qr[8 + d0], p0, 0, 0, 0);
;         p1 = __builtin_amdgcn_mfma_f32_32x32x16_bf16(b1, qr[8 + d0], p1, 0, 0, 0); }
; }
	ds_read_b128 v[70:73], v200 offset:32768
	ds_read_b128 v[66:69], v200 offset:41472
	ds_read_b128 v[230:233], v200 offset:32800
	ds_read_b128 v[234:237], v200 offset:41504
	ds_read_b128 v[242:245], v200 offset:32832
	ds_read_b128 v[246:249], v200 offset:41536
	v_exp_f32_e32 v166, v166
	v_exp_f32_e32 v180, v180
	v_exp_f32_e32 v167, v167
	v_exp_f32_e32 v179, v179
	s_waitcnt lgkmcnt(4)
	v_mfma_f32_32x32x16_bf16 v[82:97], v[70:73], v[142:145], 0
	v_exp_f32_e32 v168, v168
	v_exp_f32_e32 v178, v178
	v_exp_f32_e32 v169, v169
	v_exp_f32_e32 v177, v177
	v_mfma_f32_32x32x16_bf16 v[66:81], v[66:69], v[142:145], 0
	v_exp_f32_e32 v170, v170
	v_exp_f32_e32 v176, v176
	v_exp_f32_e32 v171, v171
	v_exp_f32_e32 v175, v175
	s_waitcnt lgkmcnt(2)
	v_mfma_f32_32x32x16_bf16 v[66:81], v[234:237], v[138:141], v[66:81]
	v_exp_f32_e32 v172, v172
	v_exp_f32_e32 v174, v174
	v_exp_f32_e32 v173, v173
	v_exp_f32_e32 v0, v0
	v_mfma_f32_32x32x16_bf16 v[82:97], v[230:233], v[138:141], v[82:97]
	ds_read_b128 v[230:233], v200 offset:32864
	ds_read_b128 v[234:237], v200 offset:41568
	v_exp_f32_e32 v192, v225
	v_exp_f32_e32 v225, v215
	v_add_f32_e32 v215, v180, v166
	s_waitcnt lgkmcnt(2)
	v_mfma_f32_32x32x16_bf16 v[66:81], v[246:249], v[134:137], v[66:81]
	v_add_f32_e32 v215, v167, v215
	v_add_f32_e32 v215, v179, v215
	v_add_f32_e32 v215, v168, v215
	v_add_f32_e32 v215, v178, v215
	v_mfma_f32_32x32x16_bf16 v[82:97], v[242:245], v[134:137], v[82:97]
	ds_read_b128 v[242:245], v200 offset:32896
	ds_read_b128 v[246:249], v200 offset:41600
	v_add_f32_e32 v215, v169, v215
	v_add_f32_e32 v215, v177, v215
	v_add_f32_e32 v215, v170, v215
	v_add_f32_e32 v215, v176, v215
	s_waitcnt lgkmcnt(2)
	v_mfma_f32_32x32x16_bf16 v[66:81], v[234:237], v[130:133], v[66:81]
	v_add_f32_e32 v215, v171, v215
	v_add_f32_e32 v215, v175, v215
	v_exp_f32_e32 v190, v223
	v_add_f32_e32 v215, v172, v215
	v_mfma_f32_32x32x16_bf16 v[82:97], v[230:233], v[130:133], v[82:97]
	ds_read_b128 v[230:233], v200 offset:32928
	ds_read_b128 v[234:237], v200 offset:41632
	v_exp_f32_e32 v191, v224
	v_add_f32_e32 v215, v174, v215
	v_add_f32_e32 v215, v0, v215
	v_exp_f32_e32 v193, v226
	s_waitcnt lgkmcnt(2)
	v_mfma_f32_32x32x16_bf16 v[66:81], v[246:249], v[126:129], v[66:81]
	v_add_f32_e32 v215, v173, v215
	v_exp_f32_e32 v223, v227
	v_add_f32_e32 v215, v190, v215
	v_exp_f32_e32 v224, v216
	v_mfma_f32_32x32x16_bf16 v[82:97], v[242:245], v[126:129], v[82:97]
	ds_read_b128 v[242:245], v200 offset:32960
	ds_read_b128 v[246:249], v200 offset:41664
	v_add_f32_e32 v215, v191, v215
	v_exp_f32_e32 v217, v217
	v_add_f32_e32 v215, v192, v215
	v_exp_f32_e32 v218, v218
	s_waitcnt lgkmcnt(2)
	v_mfma_f32_32x32x16_bf16 v[66:81], v[234:237], v[122:125], v[66:81]
	v_add_f32_e32 v215, v193, v215
	v_exp_f32_e32 v219, v219
	v_add_f32_e32 v215, v223, v215
	v_mfma_f32_32x32x16_bf16 v[82:97], v[230:233], v[122:125], v[82:97]
	ds_read_b128 v[230:233], v200 offset:32992
	ds_read_b128 v[234:237], v200 offset:41696
	v_exp_f32_e32 v220, v220
	v_add_f32_e32 v215, v224, v215
	v_exp_f32_e32 v221, v221
	v_add_f32_e32 v215, v217, v215
	s_waitcnt lgkmcnt(2)
	v_mfma_f32_32x32x16_bf16 v[66:81], v[246:249], v[118:121], v[66:81]
	v_exp_f32_e32 v222, v222
	v_add_f32_e32 v215, v218, v215
	v_add_f32_e32 v215, v219, v215
	v_exp_f32_e32 v226, v228
	v_mfma_f32_32x32x16_bf16 v[82:97], v[242:245], v[118:121], v[82:97]
	ds_read_b128 v[242:245], v204
	ds_read_b128 v[246:249], v204 offset:4608
	v_add_f32_e32 v215, v220, v215
	v_exp_f32_e32 v227, v229
	v_add_f32_e32 v215, v221, v215
	v_exp_f32_e32 v181, v181
	s_waitcnt lgkmcnt(2)
	v_mfma_f32_32x32x16_bf16 v[66:81], v[234:237], v[110:113], v[66:81]
	v_add_f32_e32 v215, v222, v215
	v_add_f32_e32 v215, v225, v215
	v_add_f32_e32 v215, v226, v215
	v_add_f32_e32 v215, v227, v215
	v_mfma_f32_32x32x16_bf16 v[82:97], v[230:233], v[110:113], v[82:97]
	ds_read_b128 v[230:233], v204 offset:32
	ds_read_b128 v[234:237], v204 offset:4640
	v_add_f32_e32 v215, v181, v215
	v_mov_b32_e32 v216, v215
	v_cvt_pk_bf16_f32 v166, v166, v180
	v_cvt_pk_bf16_f32 v167, v167, v179
	s_waitcnt lgkmcnt(2)
	v_mfma_f32_32x32x16_bf16 v[66:81], v[246:249], v[114:117], v[66:81]
	v_cvt_pk_bf16_f32 v168, v168, v178
	v_cvt_pk_bf16_f32 v169, v169, v177
	v_cvt_pk_bf16_f32 v170, v170, v176
	v_cvt_pk_bf16_f32 v171, v171, v175
	v_mfma_f32_32x32x16_bf16 v[82:97], v[242:245], v[114:117], v[82:97]
	ds_read_b128 v[242:245], v204 offset:64
	ds_read_b128 v[246:249], v204 offset:4672
	v_cvt_pk_bf16_f32 v172, v172, v174
	v_cvt_pk_bf16_f32 v173, v0, v173
	v_cvt_pk_bf16_f32 v174, v190, v191
	v_cvt_pk_bf16_f32 v175, v192, v193
	s_waitcnt lgkmcnt(2)
	v_mfma_f32_32x32x16_bf16 v[82:97], v[230:233], v[106:109], v[82:97]
	v_cvt_pk_bf16_f32 v176, v223, v224
	v_cvt_pk_bf16_f32 v177, v217, v218
	v_cvt_pk_bf16_f32 v178, v219, v220
	v_cvt_pk_bf16_f32 v179, v221, v222
	v_mfma_f32_32x32x16_bf16 v[66:81], v[234:237], v[106:109], v[66:81]
	ds_read_b128 v[230:233], v204 offset:96
	ds_read_b128 v[234:237], v204 offset:4704
	v_cvt_pk_bf16_f32 v180, v225, v226
	v_cvt_pk_bf16_f32 v181, v227, v181
	v_permlane32_swap_b32_e32 v215, v216
	v_permlane32_swap_b32_e32 v166, v168
	s_waitcnt lgkmcnt(2)
	v_mfma_f32_32x32x16_bf16 v[82:97], v[242:245], v[102:105], v[82:97]
	v_permlane32_swap_b32_e32 v167, v169
	v_permlane32_swap_b32_e32 v170, v172
	v_permlane32_swap_b32_e32 v171, v173
	v_permlane32_swap_b32_e32 v174, v176
	v_mfma_f32_32x32x16_bf16 v[66:81], v[246:249], v[102:105], v[66:81]
	v_permlane32_swap_b32_e32 v175, v177
	v_permlane32_swap_b32_e32 v178, v180
	v_permlane32_swap_b32_e32 v179, v181
	s_waitcnt lgkmcnt(0)
	v_mfma_f32_32x32x16_bf16 v[82:97], v[230:233], v[98:101], v[82:97]
	v_mfma_f32_32x32x16_bf16 v[66:81], v[234:237], v[98:101], v[66:81]
	ds_read_b64_tr_b16 v[218:219], v194 offset:0x4000
	ds_read_b64_tr_b16 v[220:221], v194 offset:0x4800
	ds_read_b64_tr_b16 v[222:223], v194 offset:0x5000
	ds_read_b64_tr_b16 v[224:225], v194 offset:0x5800
	ds_read_b64_tr_b16 v[226:227], v194 offset:0x6000
	ds_read_b64_tr_b16 v[228:229], v194 offset:0x6800
	ds_read_b64_tr_b16 v[230:231], v194 offset:0x7000
	ds_read_b64_tr_b16 v[232:233], v194 offset:0x7800
	s_add_i32 s6, s82, 1
	s_cmp_lt_u32 s6, s83
	s_cselect_b64 s[90:91], -1, 0
	s_cmp_ge_u32 s6, s83
	s_cbranch_scc1 .LBB0_416
	s_add_u32 s8, s74, 0x1b98c000
	s_addc_u32 s9, s75, 0
	s_add_u32 s10, s74, 0x1b98e000
	s_addc_u32 s11, s75, 0
	s_add_u32 s12, s80, 0x18886000
	s_addc_u32 s13, s81, 0
	s_add_u32 s14, s74, 0x1d98c000
	s_addc_u32 s15, s75, 0
	s_add_u32 s16, s74, 0x1d98e000
	s_addc_u32 s17, s75, 0
	global_load_dwordx4 v[154:157], v201, s[8:9]
	global_load_dwordx4 v[158:161], v201, s[10:11]
	global_load_dwordx4 v[162:165], v199, s[12:13]
	global_load_dwordx4 v[146:149], v201, s[14:15]
	global_load_dwordx4 v[150:153], v201, s[16:17]

; __device__ __forceinline__ void partialSM(f32x16& p0, f32x16& p1, float& m_reg, float& mn, float& alpha) {
;     float pmax = p0[0];
; #pragma unroll
;     for (int r = 1; r < 16; ++r) pmax = fmaxf(pmax, p0[r]);
; #pragma unroll
;     for (int r = 0; r < 16; ++r) pmax = fmaxf(pmax, p1[r]);
;     { auto rr = __builtin_amdgcn_permlane32_swap(__float_as_uint(pmax), __float_as_uint(pmax), false, false);
;       pmax = fmaxf(__uint_as_float(rr[0]), __uint_as_float(rr[1])); }
; template <int VB>
; __device__ __forceinline__ void pv_tile(f32x16* o, int vb0, bf16x8 pa0, bf16x8 pa1, bf16x8 pa2, bf16x8 pa3) {
;     ...
;     PV_D0(0); PV_D0(1); PV_D0(2); PV_D0(3);
.LBB0_418:
	s_nop 0
	s_waitcnt lgkmcnt(6)
	v_mfma_f32_32x32x16_bf16 v[50:65], v[166:169], v[218:221], v[50:65]
	ds_read_b64_tr_b16 v[218:219], v194 offset:0x4200
	ds_read_b64_tr_b16 v[220:221], v194 offset:0x4a00
	s_waitcnt lgkmcnt(6)
	v_mfma_f32_32x32x16_bf16 v[50:65], v[170:173], v[222:225], v[50:65]
	ds_read_b64_tr_b16 v[222:223], v194 offset:0x5200
	ds_read_b64_tr_b16 v[224:225], v194 offset:0x5a00
	v_max_f32_e32 v0, v82, v83
	v_max3_f32 v0, v0, v84, v85
	s_waitcnt lgkmcnt(6)
	v_mfma_f32_32x32x16_bf16 v[50:65], v[174:177], v[226:229], v[50:65]
	ds_read_b64_tr_b16 v[226:227], v194 offset:0x6200
	ds_read_b64_tr_b16 v[228:229], v194 offset:0x6a00
	v_max3_f32 v0, v0, v86, v87
	v_max3_f32 v0, v0, v88, v89
	s_waitcnt lgkmcnt(6)
	v_mfma_f32_32x32x16_bf16 v[50:65], v[178:181], v[230:233], v[50:65]
	ds_read_b64_tr_b16 v[230:231], v194 offset:0x7200
	ds_read_b64_tr_b16 v[232:233], v194 offset:0x7a00
	v_max3_f32 v0, v0, v90, v91
	v_max3_f32 v0, v0, v92, v93
	s_waitcnt lgkmcnt(6)
	v_mfma_f32_32x32x16_bf16 v[34:49], v[166:169], v[218:221], v[34:49]
	ds_read_b64_tr_b16 v[218:219], v194 offset:0x4400
	ds_read_b64_tr_b16 v[220:221], v194 offset:0x4c00
	v_max3_f32 v0, v0, v94, v95
	v_max3_f32 v0, v0, v96, v97
	s_waitcnt lgkmcnt(6)
	v_mfma_f32_32x32x16_bf16 v[34:49], v[170:173], v[222:225], v[34:49]
	ds_read_b64_tr_b16 v[222:223], v194 offset:0x5400
	ds_read_b64_tr_b16 v[224:225], v194 offset:0x5c00
	v_max3_f32 v0, v0, v66, v67
	v_max3_f32 v0, v0, v68, v69
	s_waitcnt lgkmcnt(6)
	v_mfma_f32_32x32x16_bf16 v[34:49], v[174:177], v[226:229], v[34:49]
	ds_read_b64_tr_b16 v[226:227], v194 offset:0x6400
	ds_read_b64_tr_b16 v[228:229], v194 offset:0x6c00
	v_max3_f32 v0, v0, v70, v71
	v_max3_f32 v0, v0, v72, v73
	s_waitcnt lgkmcnt(6)
	v_mfma_f32_32x32x16_bf16 v[34:49], v[178:181], v[230:233], v[34:49]
	ds_read_b64_tr_b16 v[230:231], v194 offset:0x7400
	ds_read_b64_tr_b16 v[232:233], v194 offset:0x7c00
	v_max3_f32 v0, v0, v74, v75
	v_max3_f32 v0, v0, v76, v77
	s_waitcnt lgkmcnt(6)
	v_mfma_f32_32x32x16_bf16 v[18:33], v[166:169], v[218:221], v[18:33]
	ds_read_b64_tr_b16 v[218:219], v194 offset:0x4600
	ds_read_b64_tr_b16 v[220:221], v194 offset:0x4e00
	v_max3_f32 v0, v0, v78, v79
	v_max3_f32 v0, v0, v80, v81
	s_waitcnt lgkmcnt(6)
	v_mfma_f32_32x32x16_bf16 v[18:33], v[170:173], v[222:225], v[18:33]
	ds_read_b64_tr_b16 v[222:223], v194 offset:0x5600
	ds_read_b64_tr_b16 v[224:225], v194 offset:0x5e00
	v_mov_b32_e32 v190, v0
	s_waitcnt lgkmcnt(6)
	v_mfma_f32_32x32x16_bf16 v[18:33], v[174:177], v[226:229], v[18:33]
	ds_read_b64_tr_b16 v[226:227], v194 offset:0x6600
	ds_read_b64_tr_b16 v[228:229], v194 offset:0x6e00
	v_permlane32_swap_b32_e32 v0, v190
	s_waitcnt lgkmcnt(6)
	v_mfma_f32_32x32x16_bf16 v[18:33], v[178:181], v[230:233], v[18:33]
	ds_read_b64_tr_b16 v[230:231], v194 offset:0x7600
	ds_read_b64_tr_b16 v[232:233], v194 offset:0x7e00
	v_max_f32_e32 v0, v0, v190
	s_waitcnt lgkmcnt(6)
	v_mfma_f32_32x32x16_bf16 v[2:17], v[166:169], v[218:221], v[2:17]
	s_and_b64 vcc, exec, s[90:91]
	s_cbranch_vccnz .Lkw2_do
	s_waitcnt lgkmcnt(0)
	s_branch .Lkw2_done

; __device__ __forceinline__ void partialSM(f32x16& p0, f32x16& p1, float& m_reg, float& mn, float& alpha) {
;     float pmax = p0[0];
; #pragma unroll
;     for (int r = 1; r < 16; ++r) pmax = fmaxf(pmax, p0[r]);
; #pragma unroll
;     for (int r = 0; r < 16; ++r) pmax = fmaxf(pmax, p1[r]);
;     { auto rr = __builtin_amdgcn_permlane32_swap(__float_as_uint(pmax), __float_as_uint(pmax), false, false);
;       pmax = fmaxf(__uint_as_float(rr[0]), __uint_as_float(rr[1])); }
;     constexpr float C2 = 1.4426950408889634f * ASCALE;
;     if (__builtin_expect(__all((pmax - m_reg) * ASCALE <= ATHR), 1)) { mn = m_reg; alpha = 1.f; }
;     else { mn = fmaxf(m_reg, pmax); alpha = __builtin_amdgcn_exp2f((m_reg - mn) * C2); m_reg = mn; }
;     const float mnL = -mn * C2;
; #pragma unroll
;     for (int r = 0; r < 16; ++r) p0[r] = fmaf(p0[r], C2, mnL);
; #pragma unroll
;     for (int r = 0; r < 16; ++r) p1[r] = fmaf(p1[r], C2, mnL);
; __device__ __forceinline__ void attn_block(const ABlk& cur, char* lds, ASeam& Sm, const int tid, const int wv) {
;     ...
;     for (int t = 1; t + 1 < NT; t += 2) {
;         HALF_STEP(pB0, pB1, mnB, alB, pA0, pA1, alA, t, 1, 0, 0);
;         HALF_STEP(pA0, pA1, mnA, alA, pB0, pB1, alB, t + 1, 0, 1, 1);
.Lkw2_done:
	v_sub_f32_e32 v190, v0, v210
	v_mul_f32_e32 v190, 0x3d93cd3a, v190
	s_waitcnt lgkmcnt(7)
	v_mfma_f32_32x32x16_bf16 v[2:17], v[170:173], v[222:225], v[2:17]
	s_mov_b32 s6, 0x41000000
	v_cmp_ge_f32_e32 vcc, s6, v190
	s_waitcnt lgkmcnt(5)
	v_mfma_f32_32x32x16_bf16 v[2:17], v[174:177], v[226:229], v[2:17]
	s_cmp_eq_u64 vcc, exec
	s_cselect_b64 s[6:7], -1, 0
	s_waitcnt lgkmcnt(3)
	v_mfma_f32_32x32x16_bf16 v[2:17], v[178:181], v[230:233], v[2:17]
	s_andn2_b64 vcc, exec, s[90:91]
	s_barrier
	s_cbranch_vccnz .LBB0_420
	s_waitcnt vmcnt(0)
	ds_write_b128 v202, v[146:149] offset:16384
	s_waitcnt vmcnt(0)
	ds_write_b128 v203, v[150:153] offset:16384
.LBB0_420:
	s_waitcnt vmcnt(4)
	v_max_f32_e32 v146, v210, v0
	v_sub_f32_e32 v0, v210, v146
	v_mul_f32_e32 v0, 0x3dd53b94, v0
	v_exp_f32_e32 v0, v0
	s_nop 0
	v_cndmask_b32_e64 v0, v0, 1.0, s[6:7]
	v_cmp_gt_f32_e32 vcc, 1.0, v0
	s_cbranch_vccz .LBB0_424
	s_and_saveexec_b64 s[8:9], s[4:5]
	ds_write_b32 v195, v0 offset:128
	s_or_b64 exec, exec, s[8:9]
	s_waitcnt lgkmcnt(0)
	s_waitcnt vmcnt(3)
	ds_read_b128 v[148:151], v198 offset:224
	s_waitcnt vmcnt(2)
	ds_read_b128 v[152:155], v198 offset:192
	s_waitcnt vmcnt(1)
	ds_read_b128 v[156:159], v198 offset:160
	s_waitcnt vmcnt(0)
	ds_read_b128 v[160:163], v198 offset:128
	s_waitcnt lgkmcnt(3)
	v_pk_mul_f32 v[64:65], v[64:65], v[150:151]
	s_waitcnt lgkmcnt(2)
	v_pk_mul_f32 v[60:61], v[60:61], v[154:155]
	s_waitcnt lgkmcnt(1)
	v_pk_mul_f32 v[56:57], v[56:57], v[158:159]
	s_waitcnt lgkmcnt(0)
	v_pk_mul_f32 v[52:53], v[52:53], v[162:163]
	v_pk_mul_f32 v[62:63], v[62:63], v[148:149]
	v_pk_mul_f32 v[58:59], v[58:59], v[152:153]
	v_pk_mul_f32 v[54:55], v[54:55], v[156:157]
	v_pk_mul_f32 v[50:51], v[50:51], v[160:161]
	v_pk_mul_f32 v[48:49], v[48:49], v[150:151]
	v_pk_mul_f32 v[44:45], v[44:45], v[154:155]
	v_pk_mul_f32 v[40:41], v[40:41], v[158:159]
	v_pk_mul_f32 v[36:37], v[36:37], v[162:163]
	v_pk_mul_f32 v[46:47], v[46:47], v[148:149]
	v_pk_mul_f32 v[42:43], v[42:43], v[152:153]
	v_pk_mul_f32 v[38:39], v[38:39], v[156:157]
	v_pk_mul_f32 v[34:35], v[34:35], v[160:161]
	v_pk_mul_f32 v[32:33], v[32:33], v[150:151]
	v_pk_mul_f32 v[28:29], v[28:29], v[154:155]
	v_pk_mul_f32 v[24:25], v[24:25], v[158:159]
	v_pk_mul_f32 v[20:21], v[20:21], v[162:163]
	v_pk_mul_f32 v[30:31], v[30:31], v[148:149]
	v_pk_mul_f32 v[26:27], v[26:27], v[152:153]
	v_pk_mul_f32 v[22:23], v[22:23], v[156:157]
	v_pk_mul_f32 v[18:19], v[18:19], v[160:161]
	v_pk_mul_f32 v[16:17], v[16:17], v[150:151]
	v_pk_mul_f32 v[12:13], v[12:13], v[154:155]
	v_pk_mul_f32 v[8:9], v[8:9], v[158:159]
	v_pk_mul_f32 v[4:5], v[4:5], v[162:163]
	v_pk_mul_f32 v[14:15], v[14:15], v[148:149]
	v_pk_mul_f32 v[10:11], v[10:11], v[152:153]
	v_pk_mul_f32 v[6:7], v[6:7], v[156:157]
	v_pk_mul_f32 v[2:3], v[2:3], v[160:161]
.LBB0_424:
	s_waitcnt vmcnt(0)
	v_cndmask_b32_e64 v210, v146, v210, s[6:7]
	v_mul_f32_e32 v148, 0xbdd53b94, v210
	s_addk_i32 s70, 0x80
	v_fmamk_f32 v166, v82, 0x3dd53b94, v148
	v_fmamk_f32 v175, v83, 0x3dd53b94, v148
	v_fmamk_f32 v167, v84, 0x3dd53b94, v148
	v_fmamk_f32 v176, v85, 0x3dd53b94, v148
	v_fmamk_f32 v168, v86, 0x3dd53b94, v148
	v_fmamk_f32 v177, v87, 0x3dd53b94, v148
	v_fmamk_f32 v169, v88, 0x3dd53b94, v148
	v_fmamk_f32 v174, v89, 0x3dd53b94, v148
	v_fmamk_f32 v165, v90, 0x3dd53b94, v148
	v_fmamk_f32 v170, v91, 0x3dd53b94, v148
	v_fmamk_f32 v171, v92, 0x3dd53b94, v148
	v_fmamk_f32 v172, v93, 0x3dd53b94, v148
	v_fmamk_f32 v162, v94, 0x3dd53b94, v148
	v_fmamk_f32 v164, v95, 0x3dd53b94, v148
	v_fmamk_f32 v163, v96, 0x3dd53b94, v148
	v_fmamk_f32 v173, v97, 0x3dd53b94, v148
	s_add_u32 s76, s76, 0x8000
	s_addc_u32 s77, s77, 0
	v_pk_fma_f32 v[160:161], v[66:67], s[84:85], v[148:149] op_sel_hi:[1,0,0]
	v_add_f32_e32 v66, v211, v212
	s_add_u32 s88, s88, 0x4000
	v_fmac_f32_e32 v66, v208, v196
	v_add_f32_e32 v196, v215, v216
	s_addc_u32 s89, s89, 0
	s_add_i32 s82, s82, 2
	v_pk_fma_f32 v[158:159], v[68:69], s[84:85], v[148:149] op_sel_hi:[1,0,0]
	v_pk_fma_f32 v[154:155], v[70:71], s[84:85], v[148:149] op_sel_hi:[1,0,0]
	v_pk_fma_f32 v[150:151], v[72:73], s[84:85], v[148:149] op_sel_hi:[1,0,0]
	v_pk_fma_f32 v[146:147], v[74:75], s[84:85], v[148:149] op_sel_hi:[1,0,0]
	v_pk_fma_f32 v[156:157], v[76:77], s[84:85], v[148:149] op_sel_hi:[1,0,0]
	v_pk_fma_f32 v[152:153], v[78:79], s[84:85], v[148:149] op_sel_hi:[1,0,0]
	v_pk_fma_f32 v[148:149], v[80:81], s[84:85], v[148:149] op_sel_hi:[1,0,0]
	v_fmac_f32_e32 v196, v66, v213
	s_cmp_ge_u32 s82, s83
	v_add_u32_e32 v209, 0xffffff80, v209
	s_waitcnt lgkmcnt(0)
	s_barrier
	s_cbranch_scc1 .LBB0_426
	v_mov_b32_e32 v208, v0
	s_branch .LBB0_408
